# grid barrier: acquire-side buffer_inv issued on arrival (before the spin) instead of after the release, in all 12 XCD barriers
# speedup vs baseline: 1.0130x; 1.0130x over previous
.LBB0_165:
	s_or_b64 exec, exec, s[10:11]
	v_cvt_f32_u32_e32 v4, v2
	s_waitcnt vmcnt(0)
	v_readfirstlane_b32 s3, v3
	v_sub_u32_e32 v3, 0, v2
	v_rcp_iflag_f32_e32 v4, v4
	v_add_u32_e32 v5, s3, v1
	v_mul_f32_e32 v4, 0x4f7ffffe, v4
	v_cvt_u32_f32_e32 v4, v4
	v_mul_lo_u32 v1, v3, v4
	v_mul_hi_u32 v1, v4, v1
	v_add_u32_e32 v1, v4, v1
	v_mul_hi_u32 v1, v5, v1
	v_mul_lo_u32 v3, v1, v2
	v_sub_u32_e32 v3, v5, v3
	v_add_u32_e32 v4, 1, v1
	v_sub_u32_e32 v6, v3, v2
	v_cmp_ge_u32_e32 vcc, v3, v2
	s_nop 1
	v_cndmask_b32_e32 v1, v1, v4, vcc
	v_cndmask_b32_e32 v3, v3, v6, vcc
	v_add_u32_e32 v4, 1, v1
	v_cmp_ge_u32_e32 vcc, v3, v2
	v_add_u32_e32 v3, 1, v5
	s_nop 0
	v_cndmask_b32_e32 v1, v1, v4, vcc
	v_mul_lo_u32 v4, v2, v1
	v_add_u32_e32 v2, v4, v2
	v_cmp_ne_u32_e32 vcc, v3, v2
	s_and_saveexec_b64 s[8:9], vcc
	s_xor_b64 s[8:9], exec, s[8:9]
	s_cbranch_execz .LBB0_179
	s_waitcnt lgkmcnt(0)
	v_mov_b32_e32 v0, 0x2000
	buffer_inv sc1
	global_load_dword v0, v0, s[6:7] offset:1024 sc1
	s_add_u32 s12, s6, 0x2400
	s_addc_u32 s13, s7, 0
	s_waitcnt vmcnt(0)
	v_cmp_eq_u32_e32 vcc, v0, v1
	s_and_saveexec_b64 s[10:11], vcc
	s_cbranch_execz .LBB0_178
	s_mov_b32 s3, 1
	s_mov_b64 s[14:15], 0
	v_mov_b32_e32 v0, 0
	s_branch .LBB0_169

.LBB0_178:
	s_or_b64 exec, exec, s[10:11]
	s_waitcnt vmcnt(0)
	s_waitcnt vmcnt(0)
.LBB0_179:
	s_andn2_saveexec_b64 s[8:9], s[8:9]
	s_cbranch_execz .LBB0_199
	s_mov_b64 s[8:9], exec
	buffer_wbl2 sc1
	s_waitcnt lgkmcnt(0)
	s_waitcnt vmcnt(0)
	buffer_inv sc1
	v_mbcnt_lo_u32_b32 v1, s8, 0
	v_mbcnt_hi_u32_b32 v1, s9, v1
	v_cmp_eq_u32_e32 vcc, 0, v1
	s_and_saveexec_b64 s[10:11], vcc
	s_cbranch_execz .LBB0_182
	s_bcnt1_i32_b64 s3, s[8:9]
	v_mov_b32_e32 v2, 0x3000
	v_mov_b32_e32 v3, s3
	global_atomic_add v2, v2, v3, s[54:55] offset:1024 sc0

.LBB0_196:
	s_or_b64 exec, exec, s[8:9]
	s_mov_b64 s[8:9], exec
	v_mbcnt_lo_u32_b32 v0, s8, 0
	v_mbcnt_hi_u32_b32 v0, s9, v0
	v_cmp_eq_u32_e32 vcc, 0, v0
	s_waitcnt vmcnt(0)
	s_and_saveexec_b64 s[10:11], vcc
	s_cbranch_execz .LBB0_198
	s_bcnt1_i32_b64 s3, s[8:9]
	v_mov_b32_e32 v0, 0x2000
	v_mov_b32_e32 v1, s3
	global_atomic_add v0, v1, s[6:7] offset:1024

.LBB0_438:
	s_or_b64 exec, exec, s[8:9]
	v_cvt_f32_u32_e32 v4, v2
	s_waitcnt vmcnt(0)
	v_readfirstlane_b32 s3, v3
	v_sub_u32_e32 v3, 0, v2
	v_rcp_iflag_f32_e32 v4, v4
	v_add_u32_e32 v5, s3, v1
	v_mul_f32_e32 v4, 0x4f7ffffe, v4
	v_cvt_u32_f32_e32 v4, v4
	v_mul_lo_u32 v1, v3, v4
	v_mul_hi_u32 v1, v4, v1
	v_add_u32_e32 v1, v4, v1
	v_mul_hi_u32 v1, v5, v1
	v_mul_lo_u32 v3, v1, v2
	v_sub_u32_e32 v3, v5, v3
	v_add_u32_e32 v4, 1, v1
	v_cmp_ge_u32_e32 vcc, v3, v2
	s_nop 1
	v_cndmask_b32_e32 v1, v1, v4, vcc
	v_sub_u32_e32 v4, v3, v2
	v_cndmask_b32_e32 v3, v3, v4, vcc
	v_add_u32_e32 v4, 1, v1
	v_cmp_ge_u32_e32 vcc, v3, v2
	v_add_u32_e32 v3, 1, v5
	s_nop 0
	v_cndmask_b32_e32 v1, v1, v4, vcc
	v_mul_lo_u32 v4, v2, v1
	v_add_u32_e32 v2, v4, v2
	v_cmp_ne_u32_e32 vcc, v3, v2
	s_and_saveexec_b64 s[6:7], vcc
	s_xor_b64 s[6:7], exec, s[6:7]
	s_cbranch_execz .LBB0_452
	s_waitcnt lgkmcnt(0)
	v_mov_b32_e32 v0, 0x2000
	buffer_inv sc1
	global_load_dword v0, v0, s[4:5] offset:1024 sc1
	s_add_u32 s10, s4, 0x2400
	s_addc_u32 s11, s5, 0
	s_waitcnt vmcnt(0)
	v_cmp_eq_u32_e32 vcc, v0, v1
	s_and_saveexec_b64 s[8:9], vcc
	s_cbranch_execz .LBB0_451
	s_mov_b32 s3, 1
	s_mov_b64 s[12:13], 0
	v_mov_b32_e32 v0, 0
	s_branch .LBB0_442

.LBB0_451:
	s_or_b64 exec, exec, s[8:9]
	s_waitcnt vmcnt(0)
	s_waitcnt vmcnt(0)
.LBB0_452:
	s_andn2_saveexec_b64 s[6:7], s[6:7]
	s_cbranch_execz .LBB0_472
	s_mov_b64 s[6:7], exec
	buffer_wbl2 sc1
	s_waitcnt lgkmcnt(0)
	s_waitcnt vmcnt(0)
	buffer_inv sc1
	v_mbcnt_lo_u32_b32 v1, s6, 0
	v_mbcnt_hi_u32_b32 v1, s7, v1
	v_cmp_eq_u32_e32 vcc, 0, v1
	s_and_saveexec_b64 s[8:9], vcc
	s_cbranch_execz .LBB0_455
	s_bcnt1_i32_b64 s3, s[6:7]
	v_mov_b32_e32 v2, 0x3000
	v_mov_b32_e32 v3, s3
	global_atomic_add v2, v2, v3, s[54:55] offset:1024 sc0

.LBB0_469:
	s_or_b64 exec, exec, s[6:7]
	s_mov_b64 s[6:7], exec
	v_mbcnt_lo_u32_b32 v0, s6, 0
	v_mbcnt_hi_u32_b32 v0, s7, v0
	v_cmp_eq_u32_e32 vcc, 0, v0
	s_waitcnt vmcnt(0)
	s_and_saveexec_b64 s[8:9], vcc
	s_cbranch_execz .LBB0_471
	s_bcnt1_i32_b64 s3, s[6:7]
	v_mov_b32_e32 v0, 0x2000
	v_mov_b32_e32 v1, s3
	global_atomic_add v0, v1, s[4:5] offset:1024

.LBB0_818:
	s_or_b64 exec, exec, s[8:9]
	v_cvt_f32_u32_e32 v144, v142
	s_waitcnt vmcnt(0)
	v_readfirstlane_b32 s3, v143
	v_sub_u32_e32 v143, 0, v142
	v_rcp_iflag_f32_e32 v144, v144
	v_add_u32_e32 v145, s3, v141
	v_mul_f32_e32 v144, 0x4f7ffffe, v144
	v_cvt_u32_f32_e32 v144, v144
	v_mul_lo_u32 v141, v143, v144
	v_mul_hi_u32 v141, v144, v141
	v_add_u32_e32 v141, v144, v141
	v_mul_hi_u32 v141, v145, v141
	v_mul_lo_u32 v143, v141, v142
	v_sub_u32_e32 v143, v145, v143
	v_add_u32_e32 v144, 1, v141
	v_cmp_ge_u32_e32 vcc, v143, v142
	s_nop 1
	v_cndmask_b32_e32 v141, v141, v144, vcc
	v_sub_u32_e32 v144, v143, v142
	v_cndmask_b32_e32 v143, v143, v144, vcc
	v_add_u32_e32 v144, 1, v141
	v_cmp_ge_u32_e32 vcc, v143, v142
	v_add_u32_e32 v143, 1, v145
	s_nop 0
	v_cndmask_b32_e32 v141, v141, v144, vcc
	v_mul_lo_u32 v144, v142, v141
	v_add_u32_e32 v142, v144, v142
	v_cmp_ne_u32_e32 vcc, v143, v142
	s_and_saveexec_b64 s[6:7], vcc
	s_xor_b64 s[6:7], exec, s[6:7]
	s_cbranch_execz .LBB0_832
	s_waitcnt lgkmcnt(0)
	v_mov_b32_e32 v140, 0x2000
	buffer_inv sc1
	global_load_dword v140, v140, s[4:5] offset:1024 sc1
	s_add_u32 s12, s4, 0x2400
	s_addc_u32 s13, s5, 0
	s_waitcnt vmcnt(0)
	v_cmp_eq_u32_e32 vcc, v140, v141
	s_and_saveexec_b64 s[8:9], vcc
	s_cbranch_execz .LBB0_831
	s_mov_b32 s3, 1
	s_mov_b64 s[14:15], 0
	v_mov_b32_e32 v140, 0
	s_branch .LBB0_822

.LBB0_832:
	s_andn2_saveexec_b64 s[6:7], s[6:7]
	s_cbranch_execz .LBB0_852
	s_mov_b64 s[6:7], exec
	buffer_wbl2 sc1
	s_waitcnt lgkmcnt(0)
	s_waitcnt vmcnt(0)
	buffer_inv sc1
	v_mbcnt_lo_u32_b32 v141, s6, 0
	v_mbcnt_hi_u32_b32 v141, s7, v141
	v_cmp_eq_u32_e32 vcc, 0, v141
	s_and_saveexec_b64 s[8:9], vcc
	s_cbranch_execz .LBB0_835
	s_bcnt1_i32_b64 s3, s[6:7]
	v_mov_b32_e32 v142, 0x3000
	v_mov_b32_e32 v143, s3
	global_atomic_add v142, v142, v143, s[54:55] offset:1024 sc0

.LBB0_849:
	s_or_b64 exec, exec, s[6:7]
	s_mov_b64 s[6:7], exec
	v_mbcnt_lo_u32_b32 v140, s6, 0
	v_mbcnt_hi_u32_b32 v140, s7, v140
	v_cmp_eq_u32_e32 vcc, 0, v140
	s_waitcnt vmcnt(0)
	s_and_saveexec_b64 s[8:9], vcc
	s_cbranch_execz .LBB0_851
	s_bcnt1_i32_b64 s3, s[6:7]
	v_mov_b32_e32 v140, 0x2000
	v_mov_b32_e32 v141, s3
	global_atomic_add v140, v141, s[4:5] offset:1024

.LBB0_881:
	s_or_b64 exec, exec, s[12:13]
	v_cvt_f32_u32_e32 v4, v2
	s_waitcnt vmcnt(0)
	v_readfirstlane_b32 s3, v3
	v_sub_u32_e32 v3, 0, v2
	v_rcp_iflag_f32_e32 v4, v4
	v_add_u32_e32 v5, s3, v1
	v_mul_f32_e32 v4, 0x4f7ffffe, v4
	v_cvt_u32_f32_e32 v4, v4
	v_mul_lo_u32 v1, v3, v4
	v_mul_hi_u32 v1, v4, v1
	v_add_u32_e32 v1, v4, v1
	v_mul_hi_u32 v1, v5, v1
	v_mul_lo_u32 v3, v1, v2
	v_sub_u32_e32 v3, v5, v3
	v_add_u32_e32 v4, 1, v1
	v_cmp_ge_u32_e32 vcc, v3, v2
	s_nop 1
	v_cndmask_b32_e32 v1, v1, v4, vcc
	v_sub_u32_e32 v4, v3, v2
	v_cndmask_b32_e32 v3, v3, v4, vcc
	v_add_u32_e32 v4, 1, v1
	v_cmp_ge_u32_e32 vcc, v3, v2
	v_add_u32_e32 v3, 1, v5
	s_nop 0
	v_cndmask_b32_e32 v1, v1, v4, vcc
	v_mul_lo_u32 v4, v2, v1
	v_add_u32_e32 v2, v4, v2
	v_cmp_ne_u32_e32 vcc, v3, v2
	s_and_saveexec_b64 s[6:7], vcc
	s_xor_b64 s[6:7], exec, s[6:7]
	s_cbranch_execz .LBB0_895
	s_waitcnt lgkmcnt(0)
	v_mov_b32_e32 v0, 0x2000
	buffer_inv sc1
	global_load_dword v0, v0, s[4:5] offset:1024 sc1
	s_add_u32 s14, s4, 0x2400
	s_addc_u32 s15, s5, 0
	s_waitcnt vmcnt(0)
	v_cmp_eq_u32_e32 vcc, v0, v1
	s_and_saveexec_b64 s[12:13], vcc
	s_cbranch_execz .LBB0_894
	s_mov_b32 s3, 1
	s_mov_b64 s[16:17], 0
	v_mov_b32_e32 v0, 0
	s_branch .LBB0_885

.LBB0_894:
	s_or_b64 exec, exec, s[12:13]
	s_waitcnt vmcnt(0)
	s_waitcnt vmcnt(0)
.LBB0_895:
	s_andn2_saveexec_b64 s[6:7], s[6:7]
	s_cbranch_execz .LBB0_915
	s_mov_b64 s[6:7], exec
	buffer_wbl2 sc1
	s_waitcnt lgkmcnt(0)
	s_waitcnt vmcnt(0)
	buffer_inv sc1
	v_mbcnt_lo_u32_b32 v1, s6, 0
	v_mbcnt_hi_u32_b32 v1, s7, v1
	v_cmp_eq_u32_e32 vcc, 0, v1
	s_and_saveexec_b64 s[12:13], vcc
	s_cbranch_execz .LBB0_898
	s_bcnt1_i32_b64 s3, s[6:7]
	v_mov_b32_e32 v2, 0x3000
	v_mov_b32_e32 v3, s3
	global_atomic_add v2, v2, v3, s[54:55] offset:1024 sc0

.LBB0_912:
	s_or_b64 exec, exec, s[6:7]
	s_mov_b64 s[6:7], exec
	v_mbcnt_lo_u32_b32 v0, s6, 0
	v_mbcnt_hi_u32_b32 v0, s7, v0
	v_cmp_eq_u32_e32 vcc, 0, v0
	s_waitcnt vmcnt(0)
	s_and_saveexec_b64 s[12:13], vcc
	s_cbranch_execz .LBB0_914
	s_bcnt1_i32_b64 s3, s[6:7]
	v_mov_b32_e32 v0, 0x2000
	v_mov_b32_e32 v1, s3
	global_atomic_add v0, v1, s[4:5] offset:1024

.LBB0_948:
	s_or_b64 exec, exec, s[14:15]
	v_cvt_f32_u32_e32 v4, v2
	s_waitcnt vmcnt(0)
	v_readfirstlane_b32 s3, v3
	v_sub_u32_e32 v3, 0, v2
	v_rcp_iflag_f32_e32 v4, v4
	v_add_u32_e32 v5, s3, v1
	v_mul_f32_e32 v4, 0x4f7ffffe, v4
	v_cvt_u32_f32_e32 v4, v4
	v_mul_lo_u32 v1, v3, v4
	v_mul_hi_u32 v1, v4, v1
	v_add_u32_e32 v1, v4, v1
	v_mul_hi_u32 v1, v5, v1
	v_mul_lo_u32 v3, v1, v2
	v_sub_u32_e32 v3, v5, v3
	v_add_u32_e32 v4, 1, v1
	v_cmp_ge_u32_e32 vcc, v3, v2
	s_nop 1
	v_cndmask_b32_e32 v1, v1, v4, vcc
	v_sub_u32_e32 v4, v3, v2
	v_cndmask_b32_e32 v3, v3, v4, vcc
	v_add_u32_e32 v4, 1, v1
	v_cmp_ge_u32_e32 vcc, v3, v2
	v_add_u32_e32 v3, 1, v5
	s_nop 0
	v_cndmask_b32_e32 v1, v1, v4, vcc
	v_mul_lo_u32 v4, v2, v1
	v_add_u32_e32 v2, v4, v2
	v_cmp_ne_u32_e32 vcc, v3, v2
	s_and_saveexec_b64 s[12:13], vcc
	s_xor_b64 s[12:13], exec, s[12:13]
	s_cbranch_execz .LBB0_962
	s_waitcnt lgkmcnt(0)
	v_mov_b32_e32 v0, 0x2000
	buffer_inv sc1
	global_load_dword v0, v0, s[6:7] offset:1024 sc1
	s_add_u32 s16, s6, 0x2400
	s_addc_u32 s17, s7, 0
	s_waitcnt vmcnt(0)
	v_cmp_eq_u32_e32 vcc, v0, v1
	s_and_saveexec_b64 s[14:15], vcc
	s_cbranch_execz .LBB0_961
	s_mov_b32 s3, 1
	s_mov_b64 s[18:19], 0
	v_mov_b32_e32 v0, 0
	s_branch .LBB0_952

.LBB0_961:
	s_or_b64 exec, exec, s[14:15]
	s_waitcnt vmcnt(0)
	s_waitcnt vmcnt(0)
.LBB0_962:
	s_andn2_saveexec_b64 s[12:13], s[12:13]
	s_cbranch_execz .LBB0_982
	s_mov_b64 s[12:13], exec
	buffer_wbl2 sc1
	s_waitcnt lgkmcnt(0)
	s_waitcnt vmcnt(0)
	buffer_inv sc1
	v_mbcnt_lo_u32_b32 v1, s12, 0
	v_mbcnt_hi_u32_b32 v1, s13, v1
	v_cmp_eq_u32_e32 vcc, 0, v1
	s_and_saveexec_b64 s[14:15], vcc
	s_cbranch_execz .LBB0_965
	s_bcnt1_i32_b64 s3, s[12:13]
	v_mov_b32_e32 v2, 0x3000
	v_mov_b32_e32 v3, s3
	global_atomic_add v2, v2, v3, s[54:55] offset:1024 sc0

.LBB0_979:
	s_or_b64 exec, exec, s[12:13]
	s_mov_b64 s[12:13], exec
	v_mbcnt_lo_u32_b32 v0, s12, 0
	v_mbcnt_hi_u32_b32 v0, s13, v0
	v_cmp_eq_u32_e32 vcc, 0, v0
	s_waitcnt vmcnt(0)
	s_and_saveexec_b64 s[14:15], vcc
	s_cbranch_execz .LBB0_981
	s_bcnt1_i32_b64 s3, s[12:13]
	v_mov_b32_e32 v0, 0x2000
	v_mov_b32_e32 v1, s3
	global_atomic_add v0, v1, s[6:7] offset:1024

.LBB0_1125:
	s_or_b64 exec, exec, s[12:13]
	v_cvt_f32_u32_e32 v4, v2
	s_waitcnt vmcnt(0)
	v_readfirstlane_b32 s3, v3
	v_sub_u32_e32 v3, 0, v2
	v_rcp_iflag_f32_e32 v4, v4
	v_add_u32_e32 v5, s3, v1
	v_mul_f32_e32 v4, 0x4f7ffffe, v4
	v_cvt_u32_f32_e32 v4, v4
	v_mul_lo_u32 v1, v3, v4
	v_mul_hi_u32 v1, v4, v1
	v_add_u32_e32 v1, v4, v1
	v_mul_hi_u32 v1, v5, v1
	v_mul_lo_u32 v3, v1, v2
	v_sub_u32_e32 v3, v5, v3
	v_add_u32_e32 v4, 1, v1
	v_cmp_ge_u32_e32 vcc, v3, v2
	s_nop 1
	v_cndmask_b32_e32 v1, v1, v4, vcc
	v_sub_u32_e32 v4, v3, v2
	v_cndmask_b32_e32 v3, v3, v4, vcc
	v_add_u32_e32 v4, 1, v1
	v_cmp_ge_u32_e32 vcc, v3, v2
	v_add_u32_e32 v3, 1, v5
	s_nop 0
	v_cndmask_b32_e32 v1, v1, v4, vcc
	v_mul_lo_u32 v4, v2, v1
	v_add_u32_e32 v2, v4, v2
	v_cmp_ne_u32_e32 vcc, v3, v2
	s_and_saveexec_b64 s[10:11], vcc
	s_xor_b64 s[10:11], exec, s[10:11]
	s_cbranch_execz .LBB0_1139
	s_waitcnt lgkmcnt(0)
	v_mov_b32_e32 v0, 0x2000
	buffer_inv sc1
	global_load_dword v0, v0, s[6:7] offset:1024 sc1
	s_add_u32 s14, s6, 0x2400
	s_addc_u32 s15, s7, 0
	s_waitcnt vmcnt(0)
	v_cmp_eq_u32_e32 vcc, v0, v1
	s_and_saveexec_b64 s[12:13], vcc
	s_cbranch_execz .LBB0_1138
	s_mov_b32 s3, 1
	s_mov_b64 s[16:17], 0
	v_mov_b32_e32 v0, 0
	s_branch .LBB0_1129

.LBB0_1139:
	s_andn2_saveexec_b64 s[10:11], s[10:11]
	s_cbranch_execz .LBB0_1159
	s_mov_b64 s[10:11], exec
	buffer_wbl2 sc1
	s_waitcnt lgkmcnt(0)
	s_waitcnt vmcnt(0)
	buffer_inv sc1
	v_mbcnt_lo_u32_b32 v1, s10, 0
	v_mbcnt_hi_u32_b32 v1, s11, v1
	v_cmp_eq_u32_e32 vcc, 0, v1
	s_and_saveexec_b64 s[12:13], vcc
	s_cbranch_execz .LBB0_1142
	s_bcnt1_i32_b64 s3, s[10:11]
	v_mov_b32_e32 v2, 0x3000
	v_mov_b32_e32 v3, s3
	global_atomic_add v2, v2, v3, s[54:55] offset:1024 sc0

.LBB0_1156:
	s_or_b64 exec, exec, s[10:11]
	s_mov_b64 s[10:11], exec
	v_mbcnt_lo_u32_b32 v0, s10, 0
	v_mbcnt_hi_u32_b32 v0, s11, v0
	v_cmp_eq_u32_e32 vcc, 0, v0
	s_waitcnt vmcnt(0)
	s_and_saveexec_b64 s[12:13], vcc
	s_cbranch_execz .LBB0_1158
	s_bcnt1_i32_b64 s3, s[10:11]
	v_mov_b32_e32 v0, 0x2000
	v_mov_b32_e32 v1, s3
	global_atomic_add v0, v1, s[6:7] offset:1024

.LBB0_1209:
	s_or_b64 exec, exec, s[12:13]
	v_cvt_f32_u32_e32 v144, v142
	s_waitcnt vmcnt(0)
	v_readfirstlane_b32 s3, v143
	v_sub_u32_e32 v143, 0, v142
	v_rcp_iflag_f32_e32 v144, v144
	v_add_u32_e32 v145, s3, v141
	v_mul_f32_e32 v144, 0x4f7ffffe, v144
	v_cvt_u32_f32_e32 v144, v144
	v_mul_lo_u32 v141, v143, v144
	v_mul_hi_u32 v141, v144, v141
	v_add_u32_e32 v141, v144, v141
	v_mul_hi_u32 v141, v145, v141
	v_mul_lo_u32 v143, v141, v142
	v_sub_u32_e32 v143, v145, v143
	v_add_u32_e32 v144, 1, v141
	v_cmp_ge_u32_e32 vcc, v143, v142
	s_nop 1
	v_cndmask_b32_e32 v141, v141, v144, vcc
	v_sub_u32_e32 v144, v143, v142
	v_cndmask_b32_e32 v143, v143, v144, vcc
	v_add_u32_e32 v144, 1, v141
	v_cmp_ge_u32_e32 vcc, v143, v142
	v_add_u32_e32 v143, 1, v145
	s_nop 0
	v_cndmask_b32_e32 v141, v141, v144, vcc
	v_mul_lo_u32 v144, v142, v141
	v_add_u32_e32 v142, v144, v142
	v_cmp_ne_u32_e32 vcc, v143, v142
	s_and_saveexec_b64 s[10:11], vcc
	s_xor_b64 s[10:11], exec, s[10:11]
	s_cbranch_execz .LBB0_1223
	s_waitcnt lgkmcnt(0)
	v_mov_b32_e32 v140, 0x2000
	buffer_inv sc1
	global_load_dword v140, v140, s[6:7] offset:1024 sc1
	s_add_u32 s14, s6, 0x2400
	s_addc_u32 s15, s7, 0
	s_waitcnt vmcnt(0)
	v_cmp_eq_u32_e32 vcc, v140, v141
	s_and_saveexec_b64 s[12:13], vcc
	s_cbranch_execz .LBB0_1222
	s_mov_b32 s3, 1
	s_mov_b64 s[16:17], 0
	v_mov_b32_e32 v140, 0
	s_branch .LBB0_1213

.LBB0_1223:
	s_andn2_saveexec_b64 s[10:11], s[10:11]
	s_cbranch_execz .LBB0_1243
	s_mov_b64 s[10:11], exec
	buffer_wbl2 sc1
	s_waitcnt lgkmcnt(0)
	s_waitcnt vmcnt(0)
	buffer_inv sc1
	v_mbcnt_lo_u32_b32 v141, s10, 0
	v_mbcnt_hi_u32_b32 v141, s11, v141
	v_cmp_eq_u32_e32 vcc, 0, v141
	s_and_saveexec_b64 s[12:13], vcc
	s_cbranch_execz .LBB0_1226
	s_bcnt1_i32_b64 s3, s[10:11]
	v_mov_b32_e32 v142, 0x3000
	v_mov_b32_e32 v143, s3
	global_atomic_add v142, v142, v143, s[54:55] offset:1024 sc0

.LBB0_1240:
	s_or_b64 exec, exec, s[10:11]
	s_mov_b64 s[10:11], exec
	v_mbcnt_lo_u32_b32 v140, s10, 0
	v_mbcnt_hi_u32_b32 v140, s11, v140
	v_cmp_eq_u32_e32 vcc, 0, v140
	s_waitcnt vmcnt(0)
	s_and_saveexec_b64 s[12:13], vcc
	s_cbranch_execz .LBB0_1242
	s_bcnt1_i32_b64 s3, s[10:11]
	v_mov_b32_e32 v140, 0x2000
	v_mov_b32_e32 v141, s3
	global_atomic_add v140, v141, s[6:7] offset:1024

.LBB0_1272:
	s_or_b64 exec, exec, s[12:13]
	v_cvt_f32_u32_e32 v4, v2
	s_waitcnt vmcnt(0)
	v_readfirstlane_b32 s3, v3
	v_sub_u32_e32 v3, 0, v2
	v_rcp_iflag_f32_e32 v4, v4
	v_add_u32_e32 v5, s3, v1
	v_mul_f32_e32 v4, 0x4f7ffffe, v4
	v_cvt_u32_f32_e32 v4, v4
	v_mul_lo_u32 v1, v3, v4
	v_mul_hi_u32 v1, v4, v1
	v_add_u32_e32 v1, v4, v1
	v_mul_hi_u32 v1, v5, v1
	v_mul_lo_u32 v3, v1, v2
	v_sub_u32_e32 v3, v5, v3
	v_add_u32_e32 v4, 1, v1
	v_cmp_ge_u32_e32 vcc, v3, v2
	s_nop 1
	v_cndmask_b32_e32 v1, v1, v4, vcc
	v_sub_u32_e32 v4, v3, v2
	v_cndmask_b32_e32 v3, v3, v4, vcc
	v_add_u32_e32 v4, 1, v1
	v_cmp_ge_u32_e32 vcc, v3, v2
	v_add_u32_e32 v3, 1, v5
	s_nop 0
	v_cndmask_b32_e32 v1, v1, v4, vcc
	v_mul_lo_u32 v4, v2, v1
	v_add_u32_e32 v2, v4, v2
	v_cmp_ne_u32_e32 vcc, v3, v2
	s_and_saveexec_b64 s[10:11], vcc
	s_xor_b64 s[10:11], exec, s[10:11]
	s_cbranch_execz .LBB0_1286
	s_waitcnt lgkmcnt(0)
	v_mov_b32_e32 v0, 0x2000
	buffer_inv sc1
	global_load_dword v0, v0, s[8:9] offset:1024 sc1
	s_add_u32 s14, s8, 0x2400
	s_addc_u32 s15, s9, 0
	s_waitcnt vmcnt(0)
	v_cmp_eq_u32_e32 vcc, v0, v1
	s_and_saveexec_b64 s[12:13], vcc
	s_cbranch_execz .LBB0_1285
	s_mov_b32 s3, 1
	s_mov_b64 s[16:17], 0
	v_mov_b32_e32 v0, 0
	s_branch .LBB0_1276

.LBB0_1303:
	s_or_b64 exec, exec, s[10:11]
	s_mov_b64 s[10:11], exec
	v_mbcnt_lo_u32_b32 v0, s10, 0
	v_mbcnt_hi_u32_b32 v0, s11, v0
	v_cmp_eq_u32_e32 vcc, 0, v0
	s_waitcnt vmcnt(0)
	s_and_saveexec_b64 s[12:13], vcc
	s_cbranch_execz .LBB0_1305
	s_bcnt1_i32_b64 s3, s[10:11]
	v_mov_b32_e32 v0, 0x2000
	v_mov_b32_e32 v1, s3
	global_atomic_add v0, v1, s[8:9] offset:1024

.LBB0_1434:
	s_or_b64 exec, exec, s[10:11]
	v_cvt_f32_u32_e32 v144, v142
	s_waitcnt vmcnt(0)
	v_readfirstlane_b32 s3, v143
	v_sub_u32_e32 v143, 0, v142
	v_rcp_iflag_f32_e32 v144, v144
	v_add_u32_e32 v145, s3, v141
	v_mul_f32_e32 v144, 0x4f7ffffe, v144
	v_cvt_u32_f32_e32 v144, v144
	v_mul_lo_u32 v141, v143, v144
	v_mul_hi_u32 v141, v144, v141
	v_add_u32_e32 v141, v144, v141
	v_mul_hi_u32 v141, v145, v141
	v_mul_lo_u32 v143, v141, v142
	v_sub_u32_e32 v143, v145, v143
	v_add_u32_e32 v144, 1, v141
	v_cmp_ge_u32_e32 vcc, v143, v142
	s_nop 1
	v_cndmask_b32_e32 v141, v141, v144, vcc
	v_sub_u32_e32 v144, v143, v142
	v_cndmask_b32_e32 v143, v143, v144, vcc
	v_add_u32_e32 v144, 1, v141
	v_cmp_ge_u32_e32 vcc, v143, v142
	v_add_u32_e32 v143, 1, v145
	s_nop 0
	v_cndmask_b32_e32 v141, v141, v144, vcc
	v_mul_lo_u32 v144, v142, v141
	v_add_u32_e32 v142, v144, v142
	v_cmp_ne_u32_e32 vcc, v143, v142
	s_and_saveexec_b64 s[8:9], vcc
	s_xor_b64 s[8:9], exec, s[8:9]
	s_cbranch_execz .LBB0_1448
	s_waitcnt lgkmcnt(0)
	v_mov_b32_e32 v140, 0x2000
	buffer_inv sc1
	global_load_dword v140, v140, s[4:5] offset:1024 sc1
	s_add_u32 s12, s4, 0x2400
	s_addc_u32 s13, s5, 0
	s_waitcnt vmcnt(0)
	v_cmp_eq_u32_e32 vcc, v140, v141
	s_and_saveexec_b64 s[10:11], vcc
	s_cbranch_execz .LBB0_1447
	s_mov_b32 s3, 1
	s_mov_b64 s[14:15], 0
	v_mov_b32_e32 v140, 0
	s_branch .LBB0_1438

.LBB0_1448:
	s_andn2_saveexec_b64 s[8:9], s[8:9]
	s_cbranch_execz .LBB0_1468
	s_mov_b64 s[8:9], exec
	buffer_wbl2 sc1
	s_waitcnt lgkmcnt(0)
	s_waitcnt vmcnt(0)
	buffer_inv sc1
	v_mbcnt_lo_u32_b32 v141, s8, 0
	v_mbcnt_hi_u32_b32 v141, s9, v141
	v_cmp_eq_u32_e32 vcc, 0, v141
	s_and_saveexec_b64 s[10:11], vcc
	s_cbranch_execz .LBB0_1451
	s_bcnt1_i32_b64 s3, s[8:9]
	v_mov_b32_e32 v142, 0x3000
	v_mov_b32_e32 v143, s3
	global_atomic_add v142, v142, v143, s[54:55] offset:1024 sc0

.LBB0_1465:
	s_or_b64 exec, exec, s[8:9]
	s_mov_b64 s[8:9], exec
	v_mbcnt_lo_u32_b32 v140, s8, 0
	v_mbcnt_hi_u32_b32 v140, s9, v140
	v_cmp_eq_u32_e32 vcc, 0, v140
	s_waitcnt vmcnt(0)
	s_and_saveexec_b64 s[10:11], vcc
	s_cbranch_execz .LBB0_1467
	s_bcnt1_i32_b64 s3, s[8:9]
	v_mov_b32_e32 v140, 0x2000
	v_mov_b32_e32 v141, s3
	global_atomic_add v140, v141, s[4:5] offset:1024
